# speedup vs baseline: 1.0079x; 1.0079x over previous
; __device__ __forceinline__ unsigned cvt_pk_bf16(float lo, float hi) { const f32x2 v = {lo, hi}; const bf16x2_t b = __builtin_convertvector(v, bf16x2_t); return __builtin_bit_cast(unsigned, b); }
; __device__ __forceinline__ void softmax_pv(f32x16& s0, f32x16& s1, float& mref, f32x16& negm, float& lsum, f32x16 (&o)[2], LAS float* fac, const bf16x8 (&vf)[2][4], bool first, int r32, int hi) {
;     ...
;     float ps0 = 0.f, ps1 = 0.f;
; #pragma unroll
;     for (int r = 0; r < 16; ++r) { s0[r] = __builtin_amdgcn_exp2f(s0[r]); s1[r] = __builtin_amdgcn_exp2f(s1[r]); ps0 += s0[r]; ps1 += s1[r]; }
;     lsum += ps0 + ps1;
;     bf16x8 pa[4];
; #pragma unroll
;     for (int k = 0; k < 4; ++k) {
;         const f32x16& s = (k < 2) ? s0 : s1; const int rb = 8 * (k & 1);
;         u32x4 w; w.x = cvt_pk_bf16(s[rb + 0], s[rb + 1]); w.y = cvt_pk_bf16(s[rb + 2], s[rb + 3]); w.z = cvt_pk_bf16(s[rb + 4], s[rb + 5]); w.w = cvt_pk_bf16(s[rb + 6], s[rb + 7]);
;         pa[k] = __builtin_bit_cast(bf16x8, w);
;     }
; #pragma unroll
;     for (int k = 0; k < 4; ++k) {
;         o[0] = __builtin_amdgcn_mfma_f32_32x32x16_bf16(pa[k], vf[0][k], o[0], 0, 0, 0);
;         o[1] = __builtin_amdgcn_mfma_f32_32x32x16_bf16(pa[k], vf[1][k], o[1], 0, 0, 0);
;     }
.Ldr_cont_00:
	v_exp_f32_e32 v80, v80
	v_exp_f32_e32 v81, v81
	v_exp_f32_e32 v82, v82
	v_mfma_f32_32x32x16_bf16 v[64:79], v[238:241], v[104:107], v[194:209]
	v_exp_f32_e32 v83, v83
	v_exp_f32_e32 v84, v84
	v_exp_f32_e32 v85, v85
	v_exp_f32_e32 v86, v86
	v_exp_f32_e32 v87, v87
	v_mfma_f32_32x32x16_bf16 v[64:79], v[188:191], v[112:115], v[64:79]
	v_cvt_pk_bf16_f32 v210, v80, v81
	v_cvt_pk_bf16_f32 v211, v82, v83
	v_cvt_pk_bf16_f32 v212, v84, v85
	v_cvt_pk_bf16_f32 v213, v86, v87
	v_add_f32_e32 v214, v80, v82
	v_add_f32_e32 v215, v81, v83
	v_add_f32_e32 v214, v214, v84
	v_add_f32_e32 v215, v215, v85
	v_add_f32_e32 v214, v214, v86
	v_add_f32_e32 v215, v215, v87
.Ldr_join_00:
	ds_read_b128 v[234:237], v187 offset:4096
	ds_read_b128 v[238:241], v187 offset:4608
	ds_read_b128 v[242:245], v187 offset:6144
	ds_read_b128 v[188:191], v187 offset:6656
	s_waitcnt lgkmcnt(7)
	ds_read_b64_tr_b16 v[136:137], v163 offset:14336
	ds_read_b64_tr_b16 v[138:139], v163 offset:14848
	ds_read_b64_tr_b16 v[152:153], v163 offset:18432
	ds_read_b64_tr_b16 v[154:155], v163 offset:18944
	ds_read_b64_tr_b16 v[140:141], v163 offset:15360
	ds_read_b64_tr_b16 v[142:143], v163 offset:15872
	ds_read_b64_tr_b16 v[156:157], v163 offset:19456
	ds_read_b64_tr_b16 v[158:159], v163 offset:19968
	v_exp_f32_e32 v88, v88
	v_exp_f32_e32 v89, v89
	v_exp_f32_e32 v90, v90
	v_mfma_f32_32x32x16_bf16 v[32:47], v[210:213], v[128:131], v[32:47]
	v_exp_f32_e32 v91, v91
	v_exp_f32_e32 v92, v92
	v_exp_f32_e32 v93, v93
	v_exp_f32_e32 v94, v94
	v_exp_f32_e32 v95, v95
	v_cvt_pk_bf16_f32 v248, v88, v89
	v_cvt_pk_bf16_f32 v249, v90, v91
	v_mfma_f32_32x32x16_bf16 v[48:63], v[210:213], v[144:147], v[48:63]
	v_cvt_pk_bf16_f32 v250, v92, v93
	v_cvt_pk_bf16_f32 v251, v94, v95
	v_add_f32_e32 v214, v214, v88
	v_add_f32_e32 v215, v215, v89
	v_add_f32_e32 v214, v214, v90
	v_add_f32_e32 v215, v215, v91
	v_add_f32_e32 v214, v214, v92
	v_add_f32_e32 v215, v215, v93
	v_add_f32_e32 v214, v214, v94
	v_add_f32_e32 v215, v215, v95
	v_exp_f32_e32 v64, v64
	v_exp_f32_e32 v65, v65
	s_waitcnt lgkmcnt(12)
	v_mfma_f32_32x32x16_bf16 v[32:47], v[248:251], v[132:135], v[32:47]
	v_exp_f32_e32 v66, v66
	v_exp_f32_e32 v67, v67
	v_exp_f32_e32 v68, v68
	v_exp_f32_e32 v69, v69
	v_mfma_f32_32x32x16_bf16 v[48:63], v[248:251], v[148:151], v[48:63]
	v_exp_f32_e32 v70, v70
	v_exp_f32_e32 v71, v71
	v_cvt_pk_bf16_f32 v210, v64, v65
	v_cvt_pk_bf16_f32 v211, v66, v67
	v_cvt_pk_bf16_f32 v212, v68, v69
	v_cvt_pk_bf16_f32 v213, v70, v71
	v_add_f32_e32 v214, v214, v64
	v_add_f32_e32 v215, v215, v65
	s_waitcnt lgkmcnt(8)
	v_mfma_f32_32x32x16_bf16 v[80:95], v[234:237], v[120:123], v[218:233]
	v_add_f32_e32 v214, v214, v66
	v_add_f32_e32 v215, v215, v67
	v_add_f32_e32 v214, v214, v68
	v_add_f32_e32 v215, v215, v69
	v_add_f32_e32 v214, v214, v70
	v_add_f32_e32 v215, v215, v71
	v_exp_f32_e32 v72, v72
	v_exp_f32_e32 v73, v73
	v_mfma_f32_32x32x16_bf16 v[80:95], v[242:245], v[124:127], v[80:95]
	v_exp_f32_e32 v74, v74
	v_exp_f32_e32 v75, v75
	v_exp_f32_e32 v76, v76
	v_exp_f32_e32 v77, v77
	s_waitcnt lgkmcnt(4)
	v_mfma_f32_32x32x16_bf16 v[32:47], v[210:213], v[136:139], v[32:47]
	v_exp_f32_e32 v78, v78
	v_exp_f32_e32 v79, v79
	v_cvt_pk_bf16_f32 v248, v72, v73
	v_cvt_pk_bf16_f32 v249, v74, v75
	v_cvt_pk_bf16_f32 v250, v76, v77
	v_cvt_pk_bf16_f32 v251, v78, v79
	v_add_f32_e32 v214, v214, v72
	v_add_f32_e32 v215, v215, v73
	v_mfma_f32_32x32x16_bf16 v[48:63], v[210:213], v[152:155], v[48:63]
	v_add_f32_e32 v214, v214, v74
	v_add_f32_e32 v215, v215, v75
	v_add_f32_e32 v214, v214, v76
	v_add_f32_e32 v215, v215, v77
	v_add_f32_e32 v214, v214, v78
	v_add_f32_e32 v215, v215, v79
	v_add_f32_e32 v214, v214, v215
	v_add_f32_e32 v162, v162, v214
	s_cmp_eq_u32 s34, 0
	s_cbranch_scc1 .Ldr_first_01
.Ldr_cont_01:
	v_mfma_f32_32x32x16_bf16 v[64:79], v[238:241], v[120:123], v[218:233]
	v_exp_f32_e32 v80, v80
	v_exp_f32_e32 v81, v81
	v_exp_f32_e32 v82, v82
	v_mfma_f32_32x32x16_bf16 v[64:79], v[188:191], v[124:127], v[64:79]
	v_exp_f32_e32 v83, v83
	v_exp_f32_e32 v84, v84
	v_exp_f32_e32 v85, v85
	s_waitcnt lgkmcnt(0)
	v_mfma_f32_32x32x16_bf16 v[32:47], v[248:251], v[140:143], v[32:47]
	v_exp_f32_e32 v86, v86
	v_exp_f32_e32 v87, v87
	v_cvt_pk_bf16_f32 v210, v80, v81
	v_cvt_pk_bf16_f32 v211, v82, v83
	v_mfma_f32_32x32x16_bf16 v[48:63], v[248:251], v[156:159], v[48:63]
	v_cvt_pk_bf16_f32 v212, v84, v85
	v_cvt_pk_bf16_f32 v213, v86, v87
	v_add_f32_e32 v214, v80, v82
	v_add_f32_e32 v215, v81, v83
	v_add_f32_e32 v214, v214, v84
	v_add_f32_e32 v215, v215, v85
	v_add_f32_e32 v214, v214, v86
	v_add_f32_e32 v215, v215, v87
; #define LAS __attribute__((address_space(3)))
; __device__ __forceinline__ unsigned cvt_pk_bf16(float lo, float hi) { const f32x2 v = {lo, hi}; const bf16x2_t b = __builtin_convertvector(v, bf16x2_t); return __builtin_bit_cast(unsigned, b); }
; __device__ __forceinline__ void softmax_pv(f32x16& s0, f32x16& s1, float& mref, f32x16& negm, float& lsum, f32x16 (&o)[2], LAS float* fac, const bf16x8 (&vf)[2][4], bool first, int r32, int hi) {
;     ...
;     float ps0 = 0.f, ps1 = 0.f;
; #pragma unroll
;     for (int r = 0; r < 16; ++r) { s0[r] = __builtin_amdgcn_exp2f(s0[r]); s1[r] = __builtin_amdgcn_exp2f(s1[r]); ps0 += s0[r]; ps1 += s1[r]; }
;     lsum += ps0 + ps1;
;     bf16x8 pa[4];
; #pragma unroll
;     for (int k = 0; k < 4; ++k) {
;         const f32x16& s = (k < 2) ? s0 : s1; const int rb = 8 * (k & 1);
;         u32x4 w; w.x = cvt_pk_bf16(s[rb + 0], s[rb + 1]); w.y = cvt_pk_bf16(s[rb + 2], s[rb + 3]); w.z = cvt_pk_bf16(s[rb + 4], s[rb + 5]); w.w = cvt_pk_bf16(s[rb + 6], s[rb + 7]);
;         pa[k] = __builtin_bit_cast(bf16x8, w);
;     }
; #pragma unroll
;     for (int k = 0; k < 4; ++k) {
;         o[0] = __builtin_amdgcn_mfma_f32_32x32x16_bf16(pa[k], vf[0][k], o[0], 0, 0, 0);
;         o[1] = __builtin_amdgcn_mfma_f32_32x32x16_bf16(pa[k], vf[1][k], o[1], 0, 0, 0);
;     }
; template <bool DIFF>
; __device__ __forceinline__ void attn_item(const Params& p, int l, int I, LAS unsigned char* lds, const int tid) {
;     ...
;             bf16x8 kg[2][2];
; #pragma unroll
;             for (int d0 = 0; d0 < 2; ++d0) { kg[d0][0] = *(const LAS bf16x8*)(kb + 4096 + d0 * 2048); kg[d0][1] = *(const LAS bf16x8*)(kb + 4096 + d0 * 2048 + 512); }
; #pragma unroll
;             for (int d0 = 0; d0 < 2; ++d0) {
;                 s0 = __builtin_amdgcn_mfma_f32_32x32x16_bf16(kg[d0][0], qf[2 + d0], s0, 0, 0, 0);
;                 s1 = __builtin_amdgcn_mfma_f32_32x32x16_bf16(kg[d0][1], qf[2 + d0], s1, 0, 0, 0);
;             }
;             softmax_pv(s0, s1, mref2, negm2, l2, o2, scr + 32, vf, t == 0, r32, hi);
.Ldr_join_01:
	ds_read_b128 v[234:237], v187 offset:20480
	ds_read_b128 v[238:241], v187 offset:20992
	ds_read_b128 v[242:245], v187 offset:22528
	ds_read_b128 v[188:191], v187 offset:23040
	v_exp_f32_e32 v88, v88
	v_exp_f32_e32 v89, v89
	v_exp_f32_e32 v90, v90
	v_mfma_f32_32x32x16_bf16 v[0:15], v[210:213], v[128:131], v[0:15]
	v_exp_f32_e32 v91, v91
	v_exp_f32_e32 v92, v92
	v_exp_f32_e32 v93, v93
	v_exp_f32_e32 v94, v94
	v_exp_f32_e32 v95, v95
	v_cvt_pk_bf16_f32 v248, v88, v89
	v_cvt_pk_bf16_f32 v249, v90, v91
	v_mfma_f32_32x32x16_bf16 v[16:31], v[210:213], v[144:147], v[16:31]
	v_cvt_pk_bf16_f32 v250, v92, v93
	v_cvt_pk_bf16_f32 v251, v94, v95
	v_add_f32_e32 v214, v214, v88
	v_add_f32_e32 v215, v215, v89
	v_add_f32_e32 v214, v214, v90
	v_add_f32_e32 v215, v215, v91
	v_add_f32_e32 v214, v214, v92
	v_add_f32_e32 v215, v215, v93
	v_add_f32_e32 v214, v214, v94
	v_add_f32_e32 v215, v215, v95
	v_exp_f32_e32 v64, v64
	v_exp_f32_e32 v65, v65
	v_mfma_f32_32x32x16_bf16 v[0:15], v[248:251], v[132:135], v[0:15]
	v_exp_f32_e32 v66, v66
	v_exp_f32_e32 v67, v67
	v_exp_f32_e32 v68, v68
	v_exp_f32_e32 v69, v69
	v_mfma_f32_32x32x16_bf16 v[16:31], v[248:251], v[148:151], v[16:31]
	v_exp_f32_e32 v70, v70
	v_exp_f32_e32 v71, v71
	v_cvt_pk_bf16_f32 v210, v64, v65
	v_cvt_pk_bf16_f32 v211, v66, v67
	v_cvt_pk_bf16_f32 v212, v68, v69
	v_cvt_pk_bf16_f32 v213, v70, v71
	v_add_f32_e32 v214, v214, v64
	v_add_f32_e32 v215, v215, v65
	s_waitcnt lgkmcnt(0)
	v_mfma_f32_32x32x16_bf16 v[80:95], v[234:237], v[104:107], v[194:209]
	v_add_f32_e32 v214, v214, v66
	v_add_f32_e32 v215, v215, v67
	v_add_f32_e32 v214, v214, v68
	v_add_f32_e32 v215, v215, v69
	v_add_f32_e32 v214, v214, v70
	v_add_f32_e32 v215, v215, v71
	v_exp_f32_e32 v72, v72
	v_exp_f32_e32 v73, v73
	v_mfma_f32_32x32x16_bf16 v[80:95], v[242:245], v[112:115], v[80:95]
	v_exp_f32_e32 v74, v74
	v_exp_f32_e32 v75, v75
	v_exp_f32_e32 v76, v76
	v_exp_f32_e32 v77, v77
	v_mfma_f32_32x32x16_bf16 v[0:15], v[210:213], v[136:139], v[0:15]
	v_exp_f32_e32 v78, v78
	v_exp_f32_e32 v79, v79
	v_cvt_pk_bf16_f32 v248, v72, v73
	v_cvt_pk_bf16_f32 v249, v74, v75
	v_cvt_pk_bf16_f32 v250, v76, v77
	v_cvt_pk_bf16_f32 v251, v78, v79
	v_add_f32_e32 v214, v214, v72
	v_add_f32_e32 v215, v215, v73
	v_mfma_f32_32x32x16_bf16 v[16:31], v[210:213], v[152:155], v[16:31]
	v_add_f32_e32 v214, v214, v74
	v_add_f32_e32 v215, v215, v75
	v_add_f32_e32 v214, v214, v76
	v_add_f32_e32 v215, v215, v77
	v_add_f32_e32 v214, v214, v78
	v_add_f32_e32 v215, v215, v79
	v_add_f32_e32 v214, v214, v215
	v_add_f32_e32 v161, v161, v214
	ds_read_b64_tr_b16 v[128:129], v163 offset:32768
	ds_read_b64_tr_b16 v[130:131], v163 offset:33280
	ds_read_b64_tr_b16 v[144:145], v163 offset:36864
	ds_read_b64_tr_b16 v[146:147], v163 offset:37376
	ds_read_b64_tr_b16 v[132:133], v163 offset:33792
	ds_read_b64_tr_b16 v[134:135], v163 offset:34304
	ds_read_b64_tr_b16 v[148:149], v163 offset:37888
	ds_read_b64_tr_b16 v[150:151], v163 offset:38400
	v_mfma_f32_32x32x16_bf16 v[64:79], v[238:241], v[104:107], v[194:209]
	v_exp_f32_e32 v80, v80
	v_exp_f32_e32 v81, v81
	v_exp_f32_e32 v82, v82
	v_mfma_f32_32x32x16_bf16 v[64:79], v[188:191], v[112:115], v[64:79]
	v_exp_f32_e32 v83, v83
	v_exp_f32_e32 v84, v84
	v_exp_f32_e32 v85, v85
	v_mfma_f32_32x32x16_bf16 v[0:15], v[248:251], v[140:143], v[0:15]
	v_exp_f32_e32 v86, v86
	v_exp_f32_e32 v87, v87
	v_cvt_pk_bf16_f32 v210, v80, v81
	v_cvt_pk_bf16_f32 v211, v82, v83
	v_mfma_f32_32x32x16_bf16 v[16:31], v[248:251], v[156:159], v[16:31]
	v_cvt_pk_bf16_f32 v212, v84, v85
	v_cvt_pk_bf16_f32 v213, v86, v87
	v_add_f32_e32 v214, v80, v82
	v_add_f32_e32 v215, v81, v83
	v_add_f32_e32 v214, v214, v84
	v_add_f32_e32 v215, v215, v85
	v_add_f32_e32 v214, v214, v86
	v_add_f32_e32 v215, v215, v87
	ds_read_b128 v[234:237], v187 offset:24576
	ds_read_b128 v[238:241], v187 offset:25088
	ds_read_b128 v[242:245], v187 offset:26624
	ds_read_b128 v[188:191], v187 offset:27136
	s_waitcnt lgkmcnt(7)
	ds_read_b64_tr_b16 v[136:137], v163 offset:34816
	ds_read_b64_tr_b16 v[138:139], v163 offset:35328
	ds_read_b64_tr_b16 v[152:153], v163 offset:38912
	ds_read_b64_tr_b16 v[154:155], v163 offset:39424
	ds_read_b64_tr_b16 v[140:141], v163 offset:35840
	ds_read_b64_tr_b16 v[142:143], v163 offset:36352
	ds_read_b64_tr_b16 v[156:157], v163 offset:39936
	ds_read_b64_tr_b16 v[158:159], v163 offset:40448
	v_exp_f32_e32 v88, v88
	v_exp_f32_e32 v89, v89
	v_exp_f32_e32 v90, v90
	v_mfma_f32_32x32x16_bf16 v[32:47], v[210:213], v[128:131], v[32:47]
	v_exp_f32_e32 v91, v91
	v_exp_f32_e32 v92, v92
	v_exp_f32_e32 v93, v93
	v_exp_f32_e32 v94, v94
	v_exp_f32_e32 v95, v95
	v_cvt_pk_bf16_f32 v248, v88, v89
	v_cvt_pk_bf16_f32 v249, v90, v91
	v_mfma_f32_32x32x16_bf16 v[48:63], v[210:213], v[144:147], v[48:63]
	v_cvt_pk_bf16_f32 v250, v92, v93
	v_cvt_pk_bf16_f32 v251, v94, v95
	v_add_f32_e32 v214, v214, v88
	v_add_f32_e32 v215, v215, v89
	v_add_f32_e32 v214, v214, v90
	v_add_f32_e32 v215, v215, v91
	v_add_f32_e32 v214, v214, v92
	v_add_f32_e32 v215, v215, v93
	v_add_f32_e32 v214, v214, v94
	v_add_f32_e32 v215, v215, v95
	v_exp_f32_e32 v64, v64
	v_exp_f32_e32 v65, v65
	s_waitcnt lgkmcnt(12)
; __device__ __forceinline__ unsigned cvt_pk_bf16(float lo, float hi) { const f32x2 v = {lo, hi}; const bf16x2_t b = __builtin_convertvector(v, bf16x2_t); return __builtin_bit_cast(unsigned, b); }
; __device__ __forceinline__ int crow(int r, int hi) { return (r & 3) + 8 * (r >> 2) + 4 * hi; }
; __device__ __forceinline__ void softmax_pv(f32x16& s0, f32x16& s1, float& mref, f32x16& negm, float& lsum, f32x16 (&o)[2], LAS float* fac, const bf16x8 (&vf)[2][4], bool first, int r32, int hi) {
;     ...
;     if (__builtin_expect(first || __any(mx > 16.0f), 0)) {
;         const float d = first ? mx : fmaxf(mx, 0.f);
;         const float f = __builtin_amdgcn_exp2f(-d);
;         lsum *= f; mref += d;
; #pragma unroll
;         for (int r = 0; r < 16; ++r) { s0[r] -= d; s1[r] -= d; negm[r] = -mref; }
;         if (hi == 0) fac[r32] = f;
;         asm volatile("s_waitcnt lgkmcnt(0)" ::: "memory");
; #pragma unroll
;         for (int r = 0; r < 16; ++r) { const float ff = fac[crow(r, hi)]; o[0][r] *= ff; o[1][r] *= ff; }
;     }
;     float ps0 = 0.f, ps1 = 0.f;
; #pragma unroll
;     for (int r = 0; r < 16; ++r) { s0[r] = __builtin_amdgcn_exp2f(s0[r]); s1[r] = __builtin_amdgcn_exp2f(s1[r]); ps0 += s0[r]; ps1 += s1[r]; }
;     lsum += ps0 + ps1;
;     bf16x8 pa[4];
; #pragma unroll
;     for (int k = 0; k < 4; ++k) {
;         const f32x16& s = (k < 2) ? s0 : s1; const int rb = 8 * (k & 1);
;         u32x4 w; w.x = cvt_pk_bf16(s[rb + 0], s[rb + 1]); w.y = cvt_pk_bf16(s[rb + 2], s[rb + 3]); w.z = cvt_pk_bf16(s[rb + 4], s[rb + 5]); w.w = cvt_pk_bf16(s[rb + 6], s[rb + 7]);
;         pa[k] = __builtin_bit_cast(bf16x8, w);
;     }
; #pragma unroll
;     for (int k = 0; k < 4; ++k) {
;         o[0] = __builtin_amdgcn_mfma_f32_32x32x16_bf16(pa[k], vf[0][k], o[0], 0, 0, 0);
;         o[1] = __builtin_amdgcn_mfma_f32_32x32x16_bf16(pa[k], vf[1][k], o[1], 0, 0, 0);
;     }
	v_mfma_f32_32x32x16_bf16 v[32:47], v[248:251], v[132:135], v[32:47]
	v_exp_f32_e32 v66, v66
	v_exp_f32_e32 v67, v67
	v_exp_f32_e32 v68, v68
	v_exp_f32_e32 v69, v69
	v_mfma_f32_32x32x16_bf16 v[48:63], v[248:251], v[148:151], v[48:63]
	v_exp_f32_e32 v70, v70
	v_exp_f32_e32 v71, v71
	v_cvt_pk_bf16_f32 v210, v64, v65
	v_cvt_pk_bf16_f32 v211, v66, v67
	v_cvt_pk_bf16_f32 v212, v68, v69
	v_cvt_pk_bf16_f32 v213, v70, v71
	v_add_f32_e32 v214, v214, v64
	v_add_f32_e32 v215, v215, v65
	s_waitcnt lgkmcnt(8)
	v_mfma_f32_32x32x16_bf16 v[80:95], v[234:237], v[120:123], v[218:233]
	v_add_f32_e32 v214, v214, v66
	v_add_f32_e32 v215, v215, v67
	v_add_f32_e32 v214, v214, v68
	v_add_f32_e32 v215, v215, v69
	v_add_f32_e32 v214, v214, v70
	v_add_f32_e32 v215, v215, v71
	v_exp_f32_e32 v72, v72
	v_exp_f32_e32 v73, v73
	v_mfma_f32_32x32x16_bf16 v[80:95], v[242:245], v[124:127], v[80:95]
	v_exp_f32_e32 v74, v74
	v_exp_f32_e32 v75, v75
	v_exp_f32_e32 v76, v76
	v_exp_f32_e32 v77, v77
	s_waitcnt lgkmcnt(4)
	v_mfma_f32_32x32x16_bf16 v[32:47], v[210:213], v[136:139], v[32:47]
	v_exp_f32_e32 v78, v78
	v_exp_f32_e32 v79, v79
	v_cvt_pk_bf16_f32 v248, v72, v73
	v_cvt_pk_bf16_f32 v249, v74, v75
	v_cvt_pk_bf16_f32 v250, v76, v77
	v_cvt_pk_bf16_f32 v251, v78, v79
	v_add_f32_e32 v214, v214, v72
	v_add_f32_e32 v215, v215, v73
	v_mfma_f32_32x32x16_bf16 v[48:63], v[210:213], v[152:155], v[48:63]
	v_add_f32_e32 v214, v214, v74
	v_add_f32_e32 v215, v215, v75
	v_add_f32_e32 v214, v214, v76
	v_add_f32_e32 v215, v215, v77
	v_add_f32_e32 v214, v214, v78
	v_add_f32_e32 v215, v215, v79
	v_add_f32_e32 v214, v214, v215
	v_add_f32_e32 v162, v162, v214
	v_exp_f32_e32 v80, v80
	v_exp_f32_e32 v81, v81
	v_mfma_f32_32x32x16_bf16 v[64:79], v[238:241], v[120:123], v[218:233]
	v_exp_f32_e32 v82, v82
	v_exp_f32_e32 v83, v83
	v_exp_f32_e32 v84, v84
	v_mfma_f32_32x32x16_bf16 v[64:79], v[188:191], v[124:127], v[64:79]
	v_exp_f32_e32 v85, v85
	v_exp_f32_e32 v86, v86
	v_exp_f32_e32 v87, v87
	v_cvt_pk_bf16_f32 v210, v80, v81
	v_cvt_pk_bf16_f32 v211, v82, v83
	s_waitcnt lgkmcnt(0)
	v_mfma_f32_32x32x16_bf16 v[32:47], v[248:251], v[140:143], v[32:47]
	v_cvt_pk_bf16_f32 v212, v84, v85
	v_cvt_pk_bf16_f32 v213, v86, v87
	v_add_f32_e32 v214, v80, v82
	v_add_f32_e32 v215, v81, v83
	v_add_f32_e32 v214, v214, v84
	v_add_f32_e32 v215, v215, v85
	v_add_f32_e32 v214, v214, v86
	v_add_f32_e32 v215, v215, v87
	v_exp_f32_e32 v88, v88
	v_exp_f32_e32 v89, v89
	v_mfma_f32_32x32x16_bf16 v[48:63], v[248:251], v[156:159], v[48:63]
	v_exp_f32_e32 v90, v90
	v_exp_f32_e32 v91, v91
	v_exp_f32_e32 v92, v92
	v_exp_f32_e32 v93, v93
	v_mfma_f32_32x32x16_bf16 v[0:15], v[210:213], v[128:131], v[0:15]
	v_exp_f32_e32 v94, v94
	v_exp_f32_e32 v95, v95
	v_cvt_pk_bf16_f32 v248, v88, v89
	v_cvt_pk_bf16_f32 v249, v90, v91
	v_cvt_pk_bf16_f32 v250, v92, v93
	v_cvt_pk_bf16_f32 v251, v94, v95
	v_add_f32_e32 v214, v214, v88
	v_add_f32_e32 v215, v215, v89
	v_mfma_f32_32x32x16_bf16 v[16:31], v[210:213], v[144:147], v[16:31]
	v_add_f32_e32 v214, v214, v90
	v_add_f32_e32 v215, v215, v91
	v_add_f32_e32 v214, v214, v92
	v_add_f32_e32 v215, v215, v93
	v_add_f32_e32 v214, v214, v94
	v_add_f32_e32 v215, v215, v95
	v_exp_f32_e32 v64, v64
	v_exp_f32_e32 v65, v65
	v_exp_f32_e32 v66, v66
	v_mfma_f32_32x32x16_bf16 v[0:15], v[248:251], v[132:135], v[0:15]
	v_exp_f32_e32 v67, v67
	v_exp_f32_e32 v68, v68
	v_exp_f32_e32 v69, v69
	v_exp_f32_e32 v70, v70
	v_exp_f32_e32 v71, v71
	v_cvt_pk_bf16_f32 v210, v64, v65
	v_cvt_pk_bf16_f32 v211, v66, v67
	v_mfma_f32_32x32x16_bf16 v[16:31], v[248:251], v[148:151], v[16:31]
	v_cvt_pk_bf16_f32 v212, v68, v69
	v_cvt_pk_bf16_f32 v213, v70, v71
	v_add_f32_e32 v214, v214, v64
	v_add_f32_e32 v215, v215, v65
	v_add_f32_e32 v214, v214, v66
	v_add_f32_e32 v215, v215, v67
	v_add_f32_e32 v214, v214, v68
	v_add_f32_e32 v215, v215, v69
	v_add_f32_e32 v214, v214, v70
	v_add_f32_e32 v215, v215, v71
	v_exp_f32_e32 v72, v72
	v_exp_f32_e32 v73, v73
	v_exp_f32_e32 v74, v74
	v_mfma_f32_32x32x16_bf16 v[0:15], v[210:213], v[136:139], v[0:15]
	v_exp_f32_e32 v75, v75
	v_exp_f32_e32 v76, v76
	v_exp_f32_e32 v77, v77
	v_exp_f32_e32 v78, v78
	v_exp_f32_e32 v79, v79
	v_cvt_pk_bf16_f32 v248, v72, v73
	v_cvt_pk_bf16_f32 v249, v74, v75
	v_mfma_f32_32x32x16_bf16 v[16:31], v[210:213], v[152:155], v[16:31]
	v_cvt_pk_bf16_f32 v250, v76, v77
	v_cvt_pk_bf16_f32 v251, v78, v79
	v_add_f32_e32 v214, v214, v72
	v_add_f32_e32 v215, v215, v73
	v_add_f32_e32 v214, v214, v74
	v_add_f32_e32 v215, v215, v75
	v_add_f32_e32 v214, v214, v76
	v_add_f32_e32 v215, v215, v77
	v_add_f32_e32 v214, v214, v78
	v_add_f32_e32 v215, v215, v79
	v_add_f32_e32 v214, v214, v215
	v_add_f32_e32 v161, v161, v214
	v_mfma_f32_32x32x16_bf16 v[0:15], v[248:251], v[140:143], v[0:15]
	v_mfma_f32_32x32x16_bf16 v[16:31], v[248:251], v[156:159], v[16:31]
	v_max_f32_e32 v210, v162, v161
	v_cmp_lt_f32_e32 vcc, 0x47800000, v210
	s_cbranch_vccnz .Ldq
